# g3ns: early S3 global arrival (end of each P3 K-loop, checked in wave 1) + s_sleep removed from poll loops
# baseline (speedup 1.0000x reference)
.Llb_g3_s3:
	global_load_dword v4, v5, s[28:29] sc1
	s_waitcnt vmcnt(0)
	v_cmp_le_u32_e32 vcc, s98, v4
	s_cbranch_vccnz .Llb_g3d_s3
	s_add_i32 s99, s99, 1
	s_cmp_lt_u32 s99, 0x40000
	s_cbranch_scc1 .Llb_g3_s3
